# norm row loops: plain (write-back) stores instead of sc1 write-through, so the counted wait for the next row's loads no longer waits for write-through acks of the previous row's stores
# speedup vs baseline: 1.0013x; 1.0013x over previous
; __device__ __forceinline__ float shx(float v, int o, int lane) { return __builtin_bit_cast(float, __builtin_amdgcn_ds_bpermute((lane ^ o) << 2, __builtin_bit_cast(int, v))); }
; __device__ __forceinline__ float wave_sum(float v, int lane) {
; #pragma unroll
;     for (int o = 1; o < 64; o <<= 1) v += shx(v, o, lane);
;     return v;
; }
; template <int MODE> __device__ __forceinline__ void norm_phase(const Ptrs& P, const float* nw, int gw, int NGW, int lane) {
;     ...
;     for (; row < nrows; row += NGW) {
;         f32x4 v[8]; float ss = 0.f;
; #pragma unroll
;         for (int j = 0; j < 8; ++j) v[j] = (MODE == 1) ? xn[j] : (f32x4){bflo(hn[j].x), bfhi(hn[j].x), bflo(hn[j].y), bfhi(hn[j].y)};
;         if (row + NGW < nrows) NORM_LOAD(row + NGW);
; #pragma unroll
;         for (int j = 0; j < 8; ++j) ss += (v[j][0] * v[j][0] + v[j][1] * v[j][1]) + (v[j][2] * v[j][2] + v[j][3] * v[j][3]);
;         ss = wave_sum(ss, lane);
.LBB0_141:
	s_or_b64 exec, exec, s[10:11]
	v_and_b32_e32 v79, 0xffff0000, v54
	v_and_b32_e32 v78, 0xffff0000, v52
	v_and_b32_e32 v83, 0xffff0000, v55
	v_and_b32_e32 v82, 0xffff0000, v53
	v_lshlrev_b32_e32 v77, 16, v54
	v_lshlrev_b32_e32 v76, 16, v52
	v_lshlrev_b32_e32 v81, 16, v55
	v_lshlrev_b32_e32 v80, 16, v53
	v_lshlrev_b32_e32 v85, 16, v45
	v_lshlrev_b32_e32 v84, 16, v44
	v_and_b32_e32 v87, 0xffff0000, v45
	v_and_b32_e32 v86, 0xffff0000, v44
	v_lshlrev_b32_e32 v58, 16, v42
	v_and_b32_e32 v59, 0xffff0000, v42
	v_lshlrev_b32_e32 v42, 16, v62
	v_and_b32_e32 v92, 0xffff0000, v62
	v_lshlrev_b32_e32 v44, 16, v63
	v_and_b32_e32 v45, 0xffff0000, v63
	v_pk_mul_f32 v[62:63], v[78:79], v[78:79]
	v_pk_mul_f32 v[72:73], v[82:83], v[82:83]
	v_pk_fma_f32 v[62:63], v[76:77], v[76:77], v[62:63]
	v_pk_fma_f32 v[72:73], v[80:81], v[80:81], v[72:73]
	v_lshlrev_b32_e32 v60, 16, v43
	v_pk_add_f32 v[62:63], v[62:63], v[72:73]
	v_lshlrev_b32_e32 v54, 16, v50
	v_pk_add_f32 v[62:63], v[62:63], v[62:63] op_sel_hi:[0,1]
	v_pk_mul_f32 v[72:73], v[86:87], v[86:87]
	v_and_b32_e32 v61, 0xffff0000, v43
	v_pk_fma_f32 v[72:73], v[84:85], v[84:85], v[72:73]
	v_mul_f32_e32 v55, v58, v58
	v_mul_f32_e32 v75, v59, v59
	v_mul_f32_e32 v62, v60, v60
	v_mov_b32_e32 v74, v54
	v_and_b32_e32 v71, 0xffff0000, v50
	v_lshlrev_b32_e32 v56, 16, v51
	v_and_b32_e32 v57, 0xffff0000, v51
	v_pk_add_f32 v[72:73], v[72:73], v[72:73] op_sel_hi:[0,1]
	v_pk_fma_f32 v[88:89], v[60:61], v[60:61], v[62:63] op_sel_hi:[1,1,0]
	v_pk_add_f32 v[74:75], v[54:55], v[74:75]
	v_mul_f32_e32 v88, v71, v71
	v_mul_f32_e32 v72, v56, v56
	v_mul_f32_e32 v62, v57, v57
	v_mul_f32_e32 v90, v54, v54
	v_mov_b32_e32 v91, v75
	v_pk_add_f32 v[74:75], v[90:91], v[88:89]
	v_pk_add_f32 v[62:63], v[72:73], v[62:63]
	v_and_b32_e32 v51, 0xffff0000, v47
	v_and_b32_e32 v50, 0xffff0000, v46
	v_pk_add_f32 v[62:63], v[74:75], v[62:63]
	v_lshlrev_b32_e32 v53, 16, v47
	v_lshlrev_b32_e32 v52, 16, v46
	v_lshlrev_b32_e32 v46, 16, v48
	v_and_b32_e32 v47, 0xffff0000, v48
	v_lshlrev_b32_e32 v48, 16, v49
	v_pk_add_f32 v[62:63], v[62:63], v[62:63] op_sel_hi:[0,1]
	v_pk_mul_f32 v[72:73], v[50:51], v[50:51]
	v_and_b32_e32 v49, 0xffff0000, v49
	v_pk_fma_f32 v[72:73], v[52:53], v[52:53], v[72:73]
	v_mul_f32_e32 v43, v46, v46
	v_mul_f32_e32 v75, v47, v47
	v_mul_f32_e32 v62, v48, v48
	v_mov_b32_e32 v74, v42
	v_pk_add_f32 v[72:73], v[72:73], v[72:73] op_sel_hi:[0,1]
	v_pk_fma_f32 v[88:89], v[48:49], v[48:49], v[62:63] op_sel_hi:[1,1,0]
	v_pk_add_f32 v[74:75], v[42:43], v[74:75]
	v_mul_f32_e32 v88, v92, v92
	v_mul_f32_e32 v72, v44, v44
	v_mul_f32_e32 v62, v45, v45
	v_mul_f32_e32 v90, v42, v42
	v_mov_b32_e32 v91, v75
	v_pk_add_f32 v[74:75], v[90:91], v[88:89]
	v_pk_add_f32 v[62:63], v[72:73], v[62:63]
	v_mov_b32_e32 v90, v81
	v_pk_add_f32 v[62:63], v[74:75], v[62:63]
	s_nop 0
	v_add_f32_e32 v43, v62, v63
	ds_bpermute_b32 v55, v64, v43
	v_mov_b32_e32 v91, v83
	v_mov_b32_e32 v81, v82
	v_add_u32_e32 v31, 0x800, v31
	s_waitcnt lgkmcnt(0)
	v_add_f32_e32 v43, v43, v55
	ds_bpermute_b32 v55, v65, v43
	s_waitcnt lgkmcnt(0)
	v_add_f32_e32 v43, v43, v55
	ds_bpermute_b32 v55, v66, v43
	s_waitcnt lgkmcnt(0)
	v_add_f32_e32 v43, v43, v55
	ds_bpermute_b32 v55, v67, v43
	s_waitcnt lgkmcnt(0)
	v_add_f32_e32 v43, v43, v55
	ds_bpermute_b32 v55, v68, v43
	s_waitcnt lgkmcnt(0)
	v_add_f32_e32 v43, v43, v55
	ds_bpermute_b32 v55, v69, v43
	s_waitcnt lgkmcnt(0)
; __device__ __forceinline__ void store8_wt(void* p, u32x2w v) { asm volatile("global_store_dwordx2 %0, %1, off sc1\n\ts_nop 1" :: "v"(p), "v"(v) : "memory"); }
; __device__ __forceinline__ unsigned pk2(float lo, float hi) { f32x2_t v = {lo, hi}; bf16x2_t b = __builtin_convertvector(v, bf16x2_t); return __builtin_bit_cast(unsigned, b); }
; template <int MODE> __device__ __forceinline__ void norm_phase(const Ptrs& P, const float* nw, int gw, int NGW, int lane) {
;     ...
;         const float rstd = 1.0f / sqrtf(ss * (1.0f / DM) + EPS);
;         if (MODE == 1) {
; #pragma unroll
;             for (int j = 0; j < 8; ++j) { u32x2 w; w.x = pk2(v[j][0], v[j][1]); w.y = pk2(v[j][2], v[j][3]); pg8::store8_wt((u32x2*)(H + (size_t)row * DM) + 64 * j + lane, w); }
;         }
; #pragma unroll
;         for (int j = 0; j < 8; ++j) {
;             const f32x4 w4 = ((const f32x4*)nw)[64 * j + lane];
;             const f32x4 o = v[j] * rstd * w4;
;             if (MODE == 2) ((f32x4*)(P.out + (size_t)row * DM))[64 * j + lane] = o;
;             else { u32x2 w; w.x = pk2(o[0], o[1]); w.y = pk2(o[2], o[3]); pg8::store8_wt((u32x2*)(U + (size_t)row * DM) + 64 * j + lane, w); }
;         }
	v_add_f32_e32 v43, v43, v55
	v_fmamk_f32 v43, v43, 0x3a000000, v234
	v_mul_f32_e32 v55, 0x4f800000, v43
	v_cmp_gt_f32_e32 vcc, s17, v43
	s_nop 1
	v_cndmask_b32_e32 v43, v43, v55, vcc
	v_sqrt_f32_e32 v55, v43
	s_nop 0
	v_add_u32_e32 v62, -1, v55
	v_fma_f32 v63, -v62, v55, v43
	v_cmp_ge_f32_e64 s[36:37], 0, v63
	v_add_u32_e32 v63, 1, v55
	s_nop 0
	v_cndmask_b32_e64 v62, v55, v62, s[36:37]
	v_fma_f32 v55, -v63, v55, v43
	v_cmp_lt_f32_e64 s[36:37], 0, v55
	s_nop 1
	v_cndmask_b32_e64 v55, v62, v63, s[36:37]
	v_mul_f32_e32 v62, 0x37800000, v55
	v_cndmask_b32_e32 v55, v55, v62, vcc
	v_cmp_class_f32_e32 vcc, v43, v235
	s_nop 1
	v_cndmask_b32_e32 v43, v55, v43, vcc
	v_div_scale_f32 v55, s[10:11], v43, v43, 1.0
	v_rcp_f32_e32 v62, v55
	s_mov_b64 s[10:11], 0x200
	v_fma_f32 v63, -v55, v62, 1.0
	v_fmac_f32_e32 v62, v63, v62
	v_div_scale_f32 v63, vcc, 1.0, v43, 1.0
	v_mul_f32_e32 v88, v63, v62
	v_fma_f32 v89, -v55, v88, v63
	v_fmac_f32_e32 v88, v89, v62
	v_fma_f32 v55, -v55, v88, v63
	v_div_fmas_f32 v55, v55, v62, v88
	v_div_fixup_f32 v88, v55, v43, 1.0
	v_mov_b32_e32 v62, v77
	v_mov_b32_e32 v63, v79
	v_pk_mul_f32 v[62:63], v[62:63], v[88:89] op_sel_hi:[1,0]
	v_pk_mul_f32 v[90:91], v[90:91], v[88:89] op_sel_hi:[1,0]
	s_nop 0
	v_pk_mul_f32 v[62:63], v[128:129], v[62:63]
	v_pk_mul_f32 v[74:75], v[130:131], v[90:91]
	v_cvt_pk_bf16_f32 v62, v62, v63
	v_cvt_pk_bf16_f32 v63, v74, v75
	global_store_dwordx2 v[18:19], v[62:63], off
	s_nop 1
	s_nop 0
	v_mov_b32_e32 v77, v78
	v_pk_mul_f32 v[76:77], v[76:77], v[88:89] op_sel_hi:[1,0]
	v_pk_mul_f32 v[78:79], v[80:81], v[88:89] op_sel_hi:[1,0]
	v_lshl_add_u64 v[62:63], v[18:19], 0, s[10:11]
	s_mov_b64 s[10:11], 0x400
	v_pk_mul_f32 v[58:59], v[58:59], v[88:89] op_sel_hi:[1,0]
	v_pk_mul_f32 v[60:61], v[60:61], v[88:89] op_sel_hi:[1,0]
	v_mov_b32_e32 v55, v71
	v_pk_mul_f32 v[54:55], v[54:55], v[88:89] op_sel_hi:[1,0]
	v_pk_mul_f32 v[56:57], v[56:57], v[88:89] op_sel_hi:[1,0]
	v_pk_mul_f32 v[46:47], v[46:47], v[88:89] op_sel_hi:[1,0]
	v_pk_mul_f32 v[48:49], v[48:49], v[88:89] op_sel_hi:[1,0]
	v_mov_b32_e32 v43, v92
	v_pk_mul_f32 v[42:43], v[42:43], v[88:89] op_sel_hi:[1,0]
	v_pk_mul_f32 v[44:45], v[44:45], v[88:89] op_sel_hi:[1,0]
	s_nop 0
	v_pk_mul_f32 v[74:75], v[134:135], v[78:79]
	v_pk_mul_f32 v[72:73], v[132:133], v[76:77]
	v_mov_b32_e32 v76, v84
	v_cvt_pk_bf16_f32 v72, v72, v73
	v_cvt_pk_bf16_f32 v73, v74, v75
	global_store_dwordx2 v[62:63], v[72:73], off
	s_nop 1
	s_nop 0
	v_mov_b32_e32 v77, v86
	v_mov_b32_e32 v86, v85
	v_pk_mul_f32 v[76:77], v[88:89], v[76:77] op_sel_hi:[0,1]
	v_pk_mul_f32 v[78:79], v[88:89], v[86:87] op_sel_hi:[0,1]
	v_lshl_add_u64 v[62:63], v[18:19], 0, s[10:11]
	s_mov_b64 s[10:11], 0x600
	s_nop 0
	v_pk_mul_f32 v[74:75], v[138:139], v[78:79]
	v_pk_mul_f32 v[72:73], v[136:137], v[76:77]
	s_nop 0
	v_cvt_pk_bf16_f32 v72, v72, v73
	v_cvt_pk_bf16_f32 v73, v74, v75
	global_store_dwordx2 v[62:63], v[72:73], off
	s_nop 1
	s_nop 0
	v_lshl_add_u64 v[62:63], v[18:19], 0, s[10:11]
	s_mov_b64 s[10:11], 0x800
	s_nop 0
	v_pk_mul_f32 v[60:61], v[142:143], v[60:61]
	v_pk_mul_f32 v[58:59], v[140:141], v[58:59]
	s_nop 0
	v_cvt_pk_bf16_f32 v58, v58, v59
	v_cvt_pk_bf16_f32 v59, v60, v61
	global_store_dwordx2 v[62:63], v[58:59], off
	s_nop 1
	s_nop 0
	v_lshl_add_u64 v[62:63], v[18:19], 0, s[10:11]
	s_mov_b64 s[10:11], 0xa00
	s_nop 0
	v_pk_mul_f32 v[56:57], v[56:57], v[146:147]
	v_pk_mul_f32 v[54:55], v[54:55], v[144:145]
	v_mov_b32_e32 v60, v52
	v_cvt_pk_bf16_f32 v54, v54, v55
	v_cvt_pk_bf16_f32 v55, v56, v57
	global_store_dwordx2 v[62:63], v[54:55], off
	s_nop 1
	s_nop 0
	v_mov_b32_e32 v61, v50
	v_mov_b32_e32 v50, v53
	v_pk_mul_f32 v[52:53], v[88:89], v[60:61] op_sel_hi:[0,1]
	v_pk_mul_f32 v[50:51], v[88:89], v[50:51] op_sel_hi:[0,1]
	v_lshl_add_u64 v[58:59], v[18:19], 0, s[10:11]
	s_mov_b64 s[10:11], 0xc00
	s_waitcnt vmcnt(5)
	v_mov_b64_e32 v[62:63], v[40:41]
	s_nop 0
	v_pk_mul_f32 v[50:51], v[50:51], v[150:151]
	v_pk_mul_f32 v[52:53], v[52:53], v[148:149]
	v_lshl_add_u64 v[54:55], v[18:19], 0, s[10:11]
	v_cvt_pk_bf16_f32 v52, v52, v53
	v_cvt_pk_bf16_f32 v53, v50, v51
	global_store_dwordx2 v[58:59], v[52:53], off
	s_nop 1
	s_nop 0
	s_mov_b64 s[10:11], 0xe00
	v_lshl_add_u64 v[56:57], v[18:19], 0, s[10:11]
	s_mov_b64 s[10:11], 0x800000
	v_lshl_add_u64 v[18:19], v[18:19], 0, s[10:11]
	s_nop 0
	v_pk_mul_f32 v[48:49], v[48:49], v[154:155]
	v_pk_mul_f32 v[46:47], v[46:47], v[152:153]
	v_mov_b64_e32 v[50:51], v[32:33]
	v_cvt_pk_bf16_f32 v46, v46, v47
	v_cvt_pk_bf16_f32 v47, v48, v49
	global_store_dwordx2 v[54:55], v[46:47], off
	s_nop 1
	s_nop 0
	v_mov_b64_e32 v[48:49], v[22:23]
	v_mov_b64_e32 v[46:47], v[24:25]
	s_nop 0
	v_pk_mul_f32 v[44:45], v[44:45], v[158:159]
	v_pk_mul_f32 v[42:43], v[42:43], v[156:157]
	v_mov_b64_e32 v[52:53], v[38:39]
	v_cvt_pk_bf16_f32 v42, v42, v43
	v_cvt_pk_bf16_f32 v43, v44, v45
	global_store_dwordx2 v[56:57], v[42:43], off
	s_nop 1
	v_mov_b64_e32 v[42:43], v[34:35]
	v_mov_b64_e32 v[44:45], v[36:37]
	v_mov_b64_e32 v[54:55], v[20:21]
	s_andn2_b64 exec, exec, s[8:9]
	s_cbranch_execz .LBB0_144

; __device__ __forceinline__ void store8_wt(void* p, u32x2w v) { asm volatile("global_store_dwordx2 %0, %1, off sc1\n\ts_nop 1" :: "v"(p), "v"(v) : "memory"); }
; __device__ __forceinline__ unsigned pk2(float lo, float hi) { f32x2_t v = {lo, hi}; bf16x2_t b = __builtin_convertvector(v, bf16x2_t); return __builtin_bit_cast(unsigned, b); }
; template <int MODE> __device__ __forceinline__ void norm_phase(const Ptrs& P, const float* nw, int gw, int NGW, int lane) {
;     ...
;         f32x4 v[8]; float ss = 0.f;
; #pragma unroll
;         for (int j = 0; j < 8; ++j) v[j] = (MODE == 1) ? xn[j] : (f32x4){bflo(hn[j].x), bfhi(hn[j].x), bflo(hn[j].y), bfhi(hn[j].y)};
;         if (row + NGW < nrows) NORM_LOAD(row + NGW);
; #pragma unroll
;         for (int j = 0; j < 8; ++j) ss += (v[j][0] * v[j][0] + v[j][1] * v[j][1]) + (v[j][2] * v[j][2] + v[j][3] * v[j][3]);
;         ss = wave_sum(ss, lane);
;         const float rstd = 1.0f / sqrtf(ss * (1.0f / DM) + EPS);
;         if (MODE == 1) {
; #pragma unroll
;             for (int j = 0; j < 8; ++j) { u32x2 w; w.x = pk2(v[j][0], v[j][1]); w.y = pk2(v[j][2], v[j][3]); pg8::store8_wt((u32x2*)(H + (size_t)row * DM) + 64 * j + lane, w); }
.LBB0_153:
	s_or_b64 exec, exec, s[8:9]
	v_mov_b32_e32 v102, v63
	v_mov_b32_e32 v103, v67
	v_mov_b32_e32 v106, v65
	v_mov_b32_e32 v107, v69
	v_mov_b32_e32 v100, v62
	v_mov_b32_e32 v101, v66
	v_pk_mul_f32 v[102:103], v[102:103], v[102:103]
	v_mov_b32_e32 v104, v64
	v_mov_b32_e32 v105, v68
	v_pk_mul_f32 v[106:107], v[106:107], v[106:107]
	v_pk_fma_f32 v[100:101], v[100:101], v[100:101], v[102:103]
	v_pk_fma_f32 v[102:103], v[104:105], v[104:105], v[106:107]
	v_pk_mul_f32 v[104:105], v[42:43], v[42:43]
	v_pk_add_f32 v[100:101], v[100:101], v[102:103]
	v_pk_mul_f32 v[102:103], v[44:45], v[44:45]
	v_pk_add_f32 v[100:101], v[100:101], v[100:101] op_sel_hi:[0,1]
	v_mov_b32_e32 v106, v104
	v_mov_b32_e32 v107, v103
	v_pk_mov_b32 v[102:103], v[104:105], v[102:103] op_sel:[1,0]
	v_mul_f32_e32 v100, v22, v22
	v_pk_add_f32 v[102:103], v[102:103], v[106:107]
	v_pk_fma_f32 v[104:105], v[22:23], v[22:23], v[100:101] op_sel_hi:[1,1,0]
	v_mul_f32_e32 v100, v24, v24
	v_pk_add_f32 v[102:103], v[102:103], v[102:103] op_sel_hi:[0,1]
	v_pk_fma_f32 v[106:107], v[24:25], v[24:25], v[100:101] op_sel_hi:[1,1,0]
	v_mul_f32_e32 v104, v18, v18
	v_mul_f32_e32 v106, v19, v19
	v_mul_f32_e32 v102, v20, v20
	v_mul_f32_e32 v100, v21, v21
	v_pk_add_f32 v[104:105], v[104:105], v[106:107]
	v_pk_add_f32 v[100:101], v[102:103], v[100:101]
	v_pk_mul_f32 v[102:103], v[12:13], v[12:13]
	v_pk_add_f32 v[100:101], v[104:105], v[100:101]
	v_mov_b32_e32 v106, v102
	v_pk_add_f32 v[104:105], v[100:101], v[100:101] op_sel_hi:[0,1]
	v_pk_mul_f32 v[100:101], v[14:15], v[14:15]
	s_and_b64 s[8:9], exec, vcc
	v_mov_b32_e32 v107, v101
	v_pk_mov_b32 v[100:101], v[102:103], v[100:101] op_sel:[1,0]
	s_or_b64 s[6:7], s[8:9], s[6:7]
	v_pk_add_f32 v[100:101], v[100:101], v[106:107]
	s_mov_b32 s8, 0xefe00000
	v_pk_add_f32 v[106:107], v[100:101], v[100:101] op_sel_hi:[0,1]
	v_mul_f32_e32 v100, v8, v8
	v_pk_fma_f32 v[108:109], v[8:9], v[8:9], v[100:101] op_sel_hi:[1,1,0]
	v_mul_f32_e32 v100, v10, v10
	s_mov_b32 s9, -1
	v_pk_fma_f32 v[110:111], v[10:11], v[10:11], v[100:101] op_sel_hi:[1,1,0]
	v_lshl_add_u64 v[100:101], v[92:93], 0, s[8:9]
	s_mov_b32 s8, 0xefe00200
	v_cvt_pk_bf16_f32 v102, v66, v67
	v_cvt_pk_bf16_f32 v103, v68, v69
	s_mov_b32 s9, -1
	global_store_dwordx2 v[100:101], v[102:103], off
	s_nop 1
	v_lshl_add_u64 v[102:103], v[92:93], 0, s[8:9]
	s_mov_b32 s8, 0xefe00400
	s_mov_b32 s9, -1
	v_cvt_pk_bf16_f32 v100, v62, v63
	v_cvt_pk_bf16_f32 v101, v64, v65
	global_store_dwordx2 v[102:103], v[100:101], off
	s_nop 1
	v_lshl_add_u64 v[102:103], v[92:93], 0, s[8:9]
	s_mov_b32 s8, 0xefe00600
	s_mov_b32 s9, -1
	v_cvt_pk_bf16_f32 v100, v42, v43
	v_cvt_pk_bf16_f32 v101, v44, v45
	global_store_dwordx2 v[102:103], v[100:101], off
	s_nop 1
	v_lshl_add_u64 v[102:103], v[92:93], 0, s[8:9]
	s_mov_b32 s8, 0xefe00800
	s_mov_b32 s9, -1
	v_cvt_pk_bf16_f32 v100, v22, v23
	v_cvt_pk_bf16_f32 v101, v24, v25
	global_store_dwordx2 v[102:103], v[100:101], off
	s_nop 1
	v_lshl_add_u64 v[102:103], v[92:93], 0, s[8:9]
	s_mov_b32 s8, 0xefe00a00
	s_mov_b32 s9, -1
	v_cvt_pk_bf16_f32 v100, v18, v19
	v_cvt_pk_bf16_f32 v101, v20, v21
	global_store_dwordx2 v[102:103], v[100:101], off
	s_nop 1
	v_lshl_add_u64 v[102:103], v[92:93], 0, s[8:9]
	s_mov_b32 s8, 0xefe00c00
	s_mov_b32 s9, -1
	v_cvt_pk_bf16_f32 v100, v12, v13
	v_cvt_pk_bf16_f32 v101, v14, v15
	global_store_dwordx2 v[102:103], v[100:101], off
	s_nop 1
	v_lshl_add_u64 v[102:103], v[92:93], 0, s[8:9]
	s_mov_b32 s8, 0xefe00e00
	v_cvt_pk_bf16_f32 v100, v8, v9
	v_cvt_pk_bf16_f32 v101, v10, v11
	global_store_dwordx2 v[102:103], v[100:101], off
	s_nop 1
	s_mov_b32 s9, -1
	v_cvt_pk_bf16_f32 v100, v4, v5
	v_cvt_pk_bf16_f32 v101, v6, v7
	v_lshl_add_u64 v[102:103], v[92:93], 0, s[8:9]
	global_store_dwordx2 v[102:103], v[100:101], off
	s_nop 1
	s_nop 0
	v_mul_f32_e32 v108, v4, v4
	v_mul_f32_e32 v110, v5, v5
	v_mul_f32_e32 v106, v6, v6
	v_mul_f32_e32 v104, v7, v7
	v_pk_add_f32 v[108:109], v[108:109], v[110:111]
	v_pk_add_f32 v[104:105], v[106:107], v[104:105]
	v_add_u32_e32 v70, 0x800, v70
	v_pk_add_f32 v[104:105], v[108:109], v[104:105]
	v_add_u32_e32 v94, 0x400000, v94
	v_add_f32_e32 v73, v104, v105
	ds_bpermute_b32 v77, v17, v73
	s_waitcnt lgkmcnt(0)
	v_add_f32_e32 v73, v73, v77
	ds_bpermute_b32 v77, v71, v73
	s_waitcnt lgkmcnt(0)
	v_add_f32_e32 v73, v73, v77
	ds_bpermute_b32 v77, v95, v73
	s_waitcnt lgkmcnt(0)
	v_add_f32_e32 v73, v73, v77
	ds_bpermute_b32 v77, v96, v73
	s_waitcnt lgkmcnt(0)
	v_add_f32_e32 v73, v73, v77
	ds_bpermute_b32 v77, v97, v73
	s_waitcnt lgkmcnt(0)
	v_add_f32_e32 v73, v73, v77
	ds_bpermute_b32 v77, v98, v73
	s_waitcnt lgkmcnt(0)
; __device__ __forceinline__ void store8_wt(void* p, u32x2w v) { asm volatile("global_store_dwordx2 %0, %1, off sc1\n\ts_nop 1" :: "v"(p), "v"(v) : "memory"); }
; __device__ __forceinline__ unsigned pk2(float lo, float hi) { f32x2_t v = {lo, hi}; bf16x2_t b = __builtin_convertvector(v, bf16x2_t); return __builtin_bit_cast(unsigned, b); }
; template <int MODE> __device__ __forceinline__ void norm_phase(const Ptrs& P, const float* nw, int gw, int NGW, int lane) {
;     ...
;         const float rstd = 1.0f / sqrtf(ss * (1.0f / DM) + EPS);
;         if (MODE == 1) {
; #pragma unroll
;             for (int j = 0; j < 8; ++j) { u32x2 w; w.x = pk2(v[j][0], v[j][1]); w.y = pk2(v[j][2], v[j][3]); pg8::store8_wt((u32x2*)(H + (size_t)row * DM) + 64 * j + lane, w); }
;         }
; #pragma unroll
;         for (int j = 0; j < 8; ++j) {
;             const f32x4 w4 = ((const f32x4*)nw)[64 * j + lane];
;             const f32x4 o = v[j] * rstd * w4;
;             if (MODE == 2) ((f32x4*)(P.out + (size_t)row * DM))[64 * j + lane] = o;
;             else { u32x2 w; w.x = pk2(o[0], o[1]); w.y = pk2(o[2], o[3]); pg8::store8_wt((u32x2*)(U + (size_t)row * DM) + 64 * j + lane, w); }
;         }
	v_add_f32_e32 v73, v73, v77
	v_fmamk_f32 v73, v73, 0x3a000000, v234
	v_mul_f32_e32 v77, 0x4f800000, v73
	v_cmp_gt_f32_e32 vcc, s17, v73
	s_nop 1
	v_cndmask_b32_e32 v73, v73, v77, vcc
	v_sqrt_f32_e32 v77, v73
	s_nop 0
	v_add_u32_e32 v79, -1, v77
	v_fma_f32 v81, -v79, v77, v73
	v_cmp_ge_f32_e64 s[36:37], 0, v81
	v_add_u32_e32 v81, 1, v77
	s_nop 0
	v_cndmask_b32_e64 v79, v77, v79, s[36:37]
	v_fma_f32 v77, -v81, v77, v73
	v_cmp_lt_f32_e64 s[36:37], 0, v77
	s_nop 1
	v_cndmask_b32_e64 v77, v79, v81, s[36:37]
	v_mul_f32_e32 v79, 0x37800000, v77
	v_cndmask_b32_e32 v77, v77, v79, vcc
	v_cmp_class_f32_e32 vcc, v73, v235
	s_nop 1
	v_cndmask_b32_e32 v73, v77, v73, vcc
	v_div_scale_f32 v77, s[8:9], v73, v73, 1.0
	v_rcp_f32_e32 v79, v77
	s_mov_b64 s[8:9], 0x200
	v_fma_f32 v81, -v77, v79, 1.0
	v_fmac_f32_e32 v79, v81, v79
	v_div_scale_f32 v81, vcc, 1.0, v73, 1.0
	v_mul_f32_e32 v83, v81, v79
	v_fma_f32 v99, -v77, v83, v81
	v_fmac_f32_e32 v83, v99, v79
	v_fma_f32 v77, -v77, v83, v81
	v_div_fmas_f32 v77, v77, v79, v83
	v_div_fixup_f32 v104, v77, v73, 1.0
	v_pk_mul_f32 v[66:67], v[66:67], v[104:105] op_sel_hi:[1,0]
	v_pk_mul_f32 v[68:69], v[68:69], v[104:105] op_sel_hi:[1,0]
	s_nop 0
	v_pk_mul_f32 v[66:67], v[66:67], v[128:129]
	v_pk_mul_f32 v[68:69], v[68:69], v[130:131]
	v_cvt_pk_bf16_f32 v66, v66, v67
	v_cvt_pk_bf16_f32 v67, v68, v69
	global_store_dwordx2 v[92:93], v[66:67], off
	s_nop 1
	s_nop 0
	v_pk_mul_f32 v[62:63], v[62:63], v[104:105] op_sel_hi:[1,0]
	v_pk_mul_f32 v[64:65], v[64:65], v[104:105] op_sel_hi:[1,0]
	v_lshl_add_u64 v[100:101], v[92:93], 0, s[8:9]
	v_pk_mul_f32 v[42:43], v[42:43], v[104:105] op_sel_hi:[1,0]
	v_pk_mul_f32 v[44:45], v[44:45], v[104:105] op_sel_hi:[1,0]
	s_mov_b64 s[8:9], 0x400
	v_pk_mul_f32 v[22:23], v[22:23], v[104:105] op_sel_hi:[1,0]
	v_pk_mul_f32 v[24:25], v[24:25], v[104:105] op_sel_hi:[1,0]
	v_pk_mul_f32 v[18:19], v[18:19], v[104:105] op_sel_hi:[1,0]
	v_pk_mul_f32 v[20:21], v[20:21], v[104:105] op_sel_hi:[1,0]
	v_pk_mul_f32 v[12:13], v[12:13], v[104:105] op_sel_hi:[1,0]
	v_pk_mul_f32 v[14:15], v[14:15], v[104:105] op_sel_hi:[1,0]
	v_pk_mul_f32 v[8:9], v[8:9], v[104:105] op_sel_hi:[1,0]
	v_pk_mul_f32 v[10:11], v[10:11], v[104:105] op_sel_hi:[1,0]
	s_nop 0
	v_pk_mul_f32 v[64:65], v[64:65], v[134:135]
	v_pk_mul_f32 v[62:63], v[62:63], v[132:133]
	v_lshl_add_u64 v[66:67], v[92:93], 0, s[8:9]
	v_cvt_pk_bf16_f32 v62, v62, v63
	v_cvt_pk_bf16_f32 v63, v64, v65
	global_store_dwordx2 v[100:101], v[62:63], off
	s_nop 1
	s_nop 0
	s_mov_b64 s[8:9], 0x600
	s_nop 0
	v_pk_mul_f32 v[44:45], v[44:45], v[138:139]
	v_pk_mul_f32 v[42:43], v[42:43], v[136:137]
	v_lshl_add_u64 v[62:63], v[92:93], 0, s[8:9]
	v_cvt_pk_bf16_f32 v42, v42, v43
	v_cvt_pk_bf16_f32 v43, v44, v45
	global_store_dwordx2 v[66:67], v[42:43], off
	s_nop 1
	s_nop 0
	s_mov_b64 s[8:9], 0x800
	s_waitcnt vmcnt(11)
	v_mov_b64_e32 v[68:69], v[28:29]
	v_mov_b64_e32 v[66:67], v[26:27]
	s_nop 0
	v_pk_mul_f32 v[24:25], v[24:25], v[142:143]
	v_pk_mul_f32 v[22:23], v[22:23], v[140:141]
	v_lshl_add_u64 v[42:43], v[92:93], 0, s[8:9]
	v_cvt_pk_bf16_f32 v22, v22, v23
	v_cvt_pk_bf16_f32 v23, v24, v25
	global_store_dwordx2 v[62:63], v[22:23], off
	s_nop 1
	s_nop 0
	s_mov_b64 s[8:9], 0xa00
	v_pk_mul_f32 v[44:45], v[4:5], v[104:105] op_sel_hi:[1,0]
	v_pk_mul_f32 v[62:63], v[6:7], v[104:105] op_sel_hi:[1,0]
	v_mov_b64_e32 v[4:5], v[58:59]
	v_mov_b64_e32 v[6:7], v[60:61]
	s_nop 0
	v_pk_mul_f32 v[20:21], v[20:21], v[146:147]
	v_pk_mul_f32 v[18:19], v[18:19], v[144:145]
	v_lshl_add_u64 v[22:23], v[92:93], 0, s[8:9]
	v_cvt_pk_bf16_f32 v18, v18, v19
	v_cvt_pk_bf16_f32 v19, v20, v21
	global_store_dwordx2 v[42:43], v[18:19], off
	s_nop 1
	s_nop 0
	s_mov_b64 s[8:9], 0xc00
	s_nop 0
	v_pk_mul_f32 v[14:15], v[14:15], v[150:151]
	v_pk_mul_f32 v[12:13], v[12:13], v[148:149]
	v_lshl_add_u64 v[18:19], v[92:93], 0, s[8:9]
	v_cvt_pk_bf16_f32 v12, v12, v13
	v_cvt_pk_bf16_f32 v13, v14, v15
	global_store_dwordx2 v[22:23], v[12:13], off
	s_nop 1
	s_nop 0
	s_mov_b64 s[8:9], 0xe00
	v_lshl_add_u64 v[42:43], v[92:93], 0, s[8:9]
	s_mov_b64 s[8:9], 0x1000000
	v_lshl_add_u64 v[0:1], v[0:1], 0, s[8:9]
	s_mov_b64 s[8:9], 0x800000
	v_lshl_add_u64 v[92:93], v[92:93], 0, s[8:9]
	s_nop 0
	v_pk_mul_f32 v[10:11], v[10:11], v[154:155]
	v_pk_mul_f32 v[8:9], v[8:9], v[152:153]
	v_mov_b64_e32 v[12:13], v[50:51]
	v_cvt_pk_bf16_f32 v8, v8, v9
	v_cvt_pk_bf16_f32 v9, v10, v11
	global_store_dwordx2 v[18:19], v[8:9], off
	s_nop 1
	s_nop 0
	v_mov_b64_e32 v[8:9], v[54:55]
	v_mov_b64_e32 v[18:19], v[46:47]
	v_mov_b64_e32 v[10:11], v[56:57]
	v_mov_b64_e32 v[14:15], v[52:53]
	v_mov_b64_e32 v[20:21], v[48:49]
	s_nop 0
	v_pk_mul_f32 v[24:25], v[62:63], v[158:159]
	v_pk_mul_f32 v[22:23], v[44:45], v[156:157]
	v_mov_b64_e32 v[64:65], v[32:33]
	v_cvt_pk_bf16_f32 v22, v22, v23
	v_cvt_pk_bf16_f32 v23, v24, v25
	global_store_dwordx2 v[42:43], v[22:23], off
	s_nop 1
	v_mov_b64_e32 v[22:23], v[38:39]
	v_mov_b64_e32 v[44:45], v[36:37]
	v_mov_b64_e32 v[24:25], v[40:41]
	v_mov_b64_e32 v[42:43], v[34:35]
	v_mov_b64_e32 v[62:63], v[30:31]
	s_andn2_b64 exec, exec, s[6:7]
	s_cbranch_execz .LBB0_157

; __device__ __forceinline__ float shx(float v, int o, int lane) { return __builtin_bit_cast(float, __builtin_amdgcn_ds_bpermute((lane ^ o) << 2, __builtin_bit_cast(int, v))); }
; __device__ __forceinline__ float wave_sum(float v, int lane) {
; #pragma unroll
;     for (int o = 1; o < 64; o <<= 1) v += shx(v, o, lane);
;     return v;
; }
; template <int MODE> __device__ __forceinline__ void norm_phase(const Ptrs& P, const float* nw, int gw, int NGW, int lane) {
;     ...
;     for (; row < nrows; row += NGW) {
;         f32x4 v[8]; float ss = 0.f;
; #pragma unroll
;         for (int j = 0; j < 8; ++j) v[j] = (MODE == 1) ? xn[j] : (f32x4){bflo(hn[j].x), bfhi(hn[j].x), bflo(hn[j].y), bfhi(hn[j].y)};
;         if (row + NGW < nrows) NORM_LOAD(row + NGW);
; #pragma unroll
;         for (int j = 0; j < 8; ++j) ss += (v[j][0] * v[j][0] + v[j][1] * v[j][1]) + (v[j][2] * v[j][2] + v[j][3] * v[j][3]);
;         ss = wave_sum(ss, lane);
.LBB0_1438:
	s_or_b64 exec, exec, s[8:9]
	v_and_b32_e32 v65, 0xffff0000, v46
	v_and_b32_e32 v64, 0xffff0000, v44
	v_and_b32_e32 v69, 0xffff0000, v47
	v_and_b32_e32 v68, 0xffff0000, v45
	v_lshlrev_b32_e32 v63, 16, v46
	v_lshlrev_b32_e32 v62, 16, v44
	v_lshlrev_b32_e32 v67, 16, v47
	v_lshlrev_b32_e32 v66, 16, v45
	v_lshlrev_b32_e32 v71, 16, v41
	v_lshlrev_b32_e32 v70, 16, v40
	v_and_b32_e32 v73, 0xffff0000, v41
	v_and_b32_e32 v72, 0xffff0000, v40
	v_lshlrev_b32_e32 v50, 16, v38
	v_and_b32_e32 v51, 0xffff0000, v38
	v_lshlrev_b32_e32 v38, 16, v42
	v_and_b32_e32 v79, 0xffff0000, v42
	v_lshlrev_b32_e32 v40, 16, v43
	v_and_b32_e32 v41, 0xffff0000, v43
	v_pk_mul_f32 v[42:43], v[64:65], v[64:65]
	v_pk_mul_f32 v[58:59], v[68:69], v[68:69]
	v_pk_fma_f32 v[42:43], v[62:63], v[62:63], v[42:43]
	v_pk_fma_f32 v[58:59], v[66:67], v[66:67], v[58:59]
	v_lshlrev_b32_e32 v52, 16, v39
	v_pk_add_f32 v[42:43], v[42:43], v[58:59]
	v_lshlrev_b32_e32 v46, 16, v32
	v_pk_add_f32 v[42:43], v[42:43], v[42:43] op_sel_hi:[0,1]
	v_pk_mul_f32 v[58:59], v[72:73], v[72:73]
	v_and_b32_e32 v53, 0xffff0000, v39
	v_pk_fma_f32 v[58:59], v[70:71], v[70:71], v[58:59]
	v_mul_f32_e32 v47, v50, v50
	v_mul_f32_e32 v61, v51, v51
	v_mul_f32_e32 v42, v52, v52
	v_mov_b32_e32 v60, v46
	v_and_b32_e32 v78, 0xffff0000, v32
	v_lshlrev_b32_e32 v48, 16, v33
	v_and_b32_e32 v49, 0xffff0000, v33
	v_pk_add_f32 v[58:59], v[58:59], v[58:59] op_sel_hi:[0,1]
	v_pk_fma_f32 v[74:75], v[52:53], v[52:53], v[42:43] op_sel_hi:[1,1,0]
	v_pk_add_f32 v[60:61], v[46:47], v[60:61]
	v_mul_f32_e32 v74, v78, v78
	v_mul_f32_e32 v58, v48, v48
	v_mul_f32_e32 v42, v49, v49
	v_mul_f32_e32 v76, v46, v46
	v_mov_b32_e32 v77, v61
	v_pk_add_f32 v[60:61], v[76:77], v[74:75]
	v_pk_add_f32 v[42:43], v[58:59], v[42:43]
	v_lshlrev_b32_e32 v45, 16, v37
	v_lshlrev_b32_e32 v44, 16, v36
	v_and_b32_e32 v37, 0xffff0000, v37
	v_and_b32_e32 v36, 0xffff0000, v36
	v_pk_add_f32 v[42:43], v[60:61], v[42:43]
	v_lshlrev_b32_e32 v32, 16, v34
	v_and_b32_e32 v33, 0xffff0000, v34
	v_lshlrev_b32_e32 v34, 16, v35
	v_pk_add_f32 v[42:43], v[42:43], v[42:43] op_sel_hi:[0,1]
	v_pk_mul_f32 v[58:59], v[36:37], v[36:37]
	v_and_b32_e32 v35, 0xffff0000, v35
	v_pk_fma_f32 v[58:59], v[44:45], v[44:45], v[58:59]
	v_mul_f32_e32 v39, v32, v32
	v_mul_f32_e32 v61, v33, v33
	v_mul_f32_e32 v42, v34, v34
	v_mov_b32_e32 v60, v38
	v_pk_add_f32 v[58:59], v[58:59], v[58:59] op_sel_hi:[0,1]
	v_pk_fma_f32 v[74:75], v[34:35], v[34:35], v[42:43] op_sel_hi:[1,1,0]
	v_pk_add_f32 v[60:61], v[38:39], v[60:61]
	v_mul_f32_e32 v74, v79, v79
	v_mul_f32_e32 v58, v40, v40
	v_mul_f32_e32 v42, v41, v41
	v_mul_f32_e32 v76, v38, v38
	v_mov_b32_e32 v77, v61
	v_pk_add_f32 v[60:61], v[76:77], v[74:75]
	v_pk_add_f32 v[42:43], v[58:59], v[42:43]
	v_mov_b32_e32 v76, v67
	v_pk_add_f32 v[42:43], v[60:61], v[42:43]
	v_add_f32_e32 v39, v42, v43
	ds_bpermute_b32 v42, v1, v39
	v_mov_b32_e32 v77, v69
	v_mov_b32_e32 v67, v68
	v_add_u32_e32 v0, 0x800, v0
	s_waitcnt lgkmcnt(0)
	v_add_f32_e32 v39, v39, v42
	ds_bpermute_b32 v42, v17, v39
	s_waitcnt lgkmcnt(0)
	v_add_f32_e32 v39, v39, v42
	ds_bpermute_b32 v42, v54, v39
	s_waitcnt lgkmcnt(0)
	v_add_f32_e32 v39, v39, v42
	ds_bpermute_b32 v42, v55, v39
	s_waitcnt lgkmcnt(0)
	v_add_f32_e32 v39, v39, v42
	ds_bpermute_b32 v42, v56, v39
	s_waitcnt lgkmcnt(0)
	v_add_f32_e32 v39, v39, v42
	ds_bpermute_b32 v42, v57, v39
	s_waitcnt lgkmcnt(0)
; __device__ __forceinline__ void store8_wt(void* p, u32x2w v) { asm volatile("global_store_dwordx2 %0, %1, off sc1\n\ts_nop 1" :: "v"(p), "v"(v) : "memory"); }
; __device__ __forceinline__ unsigned pk2(float lo, float hi) { f32x2_t v = {lo, hi}; bf16x2_t b = __builtin_convertvector(v, bf16x2_t); return __builtin_bit_cast(unsigned, b); }
; template <int MODE> __device__ __forceinline__ void norm_phase(const Ptrs& P, const float* nw, int gw, int NGW, int lane) {
;     ...
;         const float rstd = 1.0f / sqrtf(ss * (1.0f / DM) + EPS);
;         if (MODE == 1) {
; #pragma unroll
;             for (int j = 0; j < 8; ++j) { u32x2 w; w.x = pk2(v[j][0], v[j][1]); w.y = pk2(v[j][2], v[j][3]); pg8::store8_wt((u32x2*)(H + (size_t)row * DM) + 64 * j + lane, w); }
;         }
; #pragma unroll
;         for (int j = 0; j < 8; ++j) {
;             const f32x4 w4 = ((const f32x4*)nw)[64 * j + lane];
;             const f32x4 o = v[j] * rstd * w4;
;             if (MODE == 2) ((f32x4*)(P.out + (size_t)row * DM))[64 * j + lane] = o;
;             else { u32x2 w; w.x = pk2(o[0], o[1]); w.y = pk2(o[2], o[3]); pg8::store8_wt((u32x2*)(U + (size_t)row * DM) + 64 * j + lane, w); }
;         }
	v_add_f32_e32 v39, v39, v42
	v_fmamk_f32 v39, v39, 0x3a000000, v234
	v_mul_f32_e32 v42, 0x4f800000, v39
	v_cmp_gt_f32_e32 vcc, s13, v39
	s_nop 1
	v_cndmask_b32_e32 v39, v39, v42, vcc
	v_sqrt_f32_e32 v42, v39
	s_nop 0
	v_add_u32_e32 v43, -1, v42
	v_fma_f32 v47, -v43, v42, v39
	v_cmp_ge_f32_e64 s[38:39], 0, v47
	v_add_u32_e32 v47, 1, v42
	s_nop 0
	v_cndmask_b32_e64 v43, v42, v43, s[38:39]
	v_fma_f32 v42, -v47, v42, v39
	v_cmp_lt_f32_e64 s[38:39], 0, v42
	s_nop 1
	v_cndmask_b32_e64 v42, v43, v47, s[38:39]
	v_mul_f32_e32 v43, 0x37800000, v42
	v_cndmask_b32_e32 v42, v42, v43, vcc
	v_cmp_class_f32_e32 vcc, v39, v235
	s_nop 1
	v_cndmask_b32_e32 v39, v42, v39, vcc
	v_div_scale_f32 v42, s[8:9], v39, v39, 1.0
	v_rcp_f32_e32 v43, v42
	s_mov_b64 s[8:9], 0x200
	v_fma_f32 v47, -v42, v43, 1.0
	v_fmac_f32_e32 v43, v47, v43
	v_div_scale_f32 v47, vcc, 1.0, v39, 1.0
	v_mul_f32_e32 v74, v47, v43
	v_fma_f32 v75, -v42, v74, v47
	v_fmac_f32_e32 v74, v75, v43
	v_fma_f32 v42, -v42, v74, v47
	v_div_fmas_f32 v42, v42, v43, v74
	v_div_fixup_f32 v74, v42, v39, 1.0
	v_mov_b32_e32 v42, v63
	v_mov_b32_e32 v43, v65
	v_pk_mul_f32 v[42:43], v[42:43], v[74:75] op_sel_hi:[1,0]
	v_pk_mul_f32 v[76:77], v[76:77], v[74:75] op_sel_hi:[1,0]
	v_pk_mul_f32 v[42:43], v[132:133], v[42:43]
	v_pk_mul_f32 v[60:61], v[134:135], v[76:77]
	v_cvt_pk_bf16_f32 v42, v42, v43
	v_cvt_pk_bf16_f32 v43, v60, v61
	global_store_dwordx2 v[12:13], v[42:43], off
	s_nop 1
	v_mov_b32_e32 v63, v64
	v_pk_mul_f32 v[62:63], v[62:63], v[74:75] op_sel_hi:[1,0]
	v_pk_mul_f32 v[64:65], v[66:67], v[74:75] op_sel_hi:[1,0]
	v_lshl_add_u64 v[42:43], v[12:13], 0, s[8:9]
	s_mov_b64 s[8:9], 0x400
	v_pk_mul_f32 v[50:51], v[50:51], v[74:75] op_sel_hi:[1,0]
	v_pk_mul_f32 v[52:53], v[52:53], v[74:75] op_sel_hi:[1,0]
	v_mov_b32_e32 v47, v78
	v_pk_mul_f32 v[46:47], v[46:47], v[74:75] op_sel_hi:[1,0]
	v_pk_mul_f32 v[48:49], v[48:49], v[74:75] op_sel_hi:[1,0]
	v_pk_mul_f32 v[32:33], v[32:33], v[74:75] op_sel_hi:[1,0]
	v_pk_mul_f32 v[34:35], v[34:35], v[74:75] op_sel_hi:[1,0]
	v_mov_b32_e32 v39, v79
	v_pk_mul_f32 v[38:39], v[38:39], v[74:75] op_sel_hi:[1,0]
	v_pk_mul_f32 v[40:41], v[40:41], v[74:75] op_sel_hi:[1,0]
	v_pk_mul_f32 v[60:61], v[138:139], v[64:65]
	v_pk_mul_f32 v[58:59], v[136:137], v[62:63]
	v_mov_b32_e32 v62, v70
	v_cvt_pk_bf16_f32 v58, v58, v59
	v_cvt_pk_bf16_f32 v59, v60, v61
	global_store_dwordx2 v[42:43], v[58:59], off
	s_nop 1
	v_mov_b32_e32 v63, v72
	v_mov_b32_e32 v72, v71
	v_pk_mul_f32 v[62:63], v[74:75], v[62:63] op_sel_hi:[0,1]
	v_pk_mul_f32 v[64:65], v[74:75], v[72:73] op_sel_hi:[0,1]
	v_lshl_add_u64 v[42:43], v[12:13], 0, s[8:9]
	s_mov_b64 s[8:9], 0x600
	v_pk_mul_f32 v[60:61], v[142:143], v[64:65]
	v_pk_mul_f32 v[58:59], v[140:141], v[62:63]
	s_nop 0
	v_cvt_pk_bf16_f32 v58, v58, v59
	v_cvt_pk_bf16_f32 v59, v60, v61
	global_store_dwordx2 v[42:43], v[58:59], off
	s_nop 1
	v_lshl_add_u64 v[42:43], v[12:13], 0, s[8:9]
	s_mov_b64 s[8:9], 0x800
	v_pk_mul_f32 v[52:53], v[146:147], v[52:53]
	v_pk_mul_f32 v[50:51], v[144:145], v[50:51]
	s_nop 0
	v_cvt_pk_bf16_f32 v50, v50, v51
	v_cvt_pk_bf16_f32 v51, v52, v53
	global_store_dwordx2 v[42:43], v[50:51], off
	s_nop 1
	v_lshl_add_u64 v[42:43], v[12:13], 0, s[8:9]
	s_mov_b64 s[8:9], 0xa00
	v_pk_mul_f32 v[48:49], v[48:49], v[150:151]
	v_pk_mul_f32 v[46:47], v[46:47], v[148:149]
	v_mov_b32_e32 v50, v44
	v_cvt_pk_bf16_f32 v46, v46, v47
	v_cvt_pk_bf16_f32 v47, v48, v49
	global_store_dwordx2 v[42:43], v[46:47], off
	s_nop 1
	v_mov_b32_e32 v51, v36
	v_mov_b32_e32 v36, v45
	v_pk_mul_f32 v[44:45], v[74:75], v[50:51] op_sel_hi:[0,1]
	v_pk_mul_f32 v[36:37], v[74:75], v[36:37] op_sel_hi:[0,1]
	v_lshl_add_u64 v[42:43], v[12:13], 0, s[8:9]
	s_mov_b64 s[8:9], 0xc00
	v_pk_mul_f32 v[36:37], v[36:37], v[154:155]
	v_pk_mul_f32 v[44:45], v[44:45], v[152:153]
	s_nop 0
	v_cvt_pk_bf16_f32 v44, v44, v45
	v_cvt_pk_bf16_f32 v45, v36, v37
	global_store_dwordx2 v[42:43], v[44:45], off
	s_nop 1
	v_lshl_add_u64 v[36:37], v[12:13], 0, s[8:9]
	s_mov_b64 s[8:9], 0xe00
	v_lshl_add_u64 v[48:49], v[12:13], 0, s[8:9]
	s_mov_b64 s[8:9], 0x800000
	v_lshl_add_u64 v[12:13], v[12:13], 0, s[8:9]
	v_pk_mul_f32 v[34:35], v[34:35], v[158:159]
	v_pk_mul_f32 v[32:33], v[32:33], v[156:157]
	s_waitcnt vmcnt(6)
	v_mov_b64_e32 v[42:43], v[14:15]
	v_cvt_pk_bf16_f32 v32, v32, v33
	v_cvt_pk_bf16_f32 v33, v34, v35
	global_store_dwordx2 v[36:37], v[32:33], off
	s_nop 1
	v_mov_b64_e32 v[34:35], v[18:19]
	v_mov_b64_e32 v[36:37], v[20:21]
	v_mov_b64_e32 v[32:33], v[22:23]
	v_pk_mul_f32 v[40:41], v[40:41], v[162:163]
	v_pk_mul_f32 v[38:39], v[38:39], v[160:161]
	v_mov_b64_e32 v[44:45], v[28:29]
	v_cvt_pk_bf16_f32 v38, v38, v39
	v_cvt_pk_bf16_f32 v39, v40, v41
	global_store_dwordx2 v[48:49], v[38:39], off
	s_nop 1
	v_mov_b64_e32 v[38:39], v[24:25]
	v_mov_b64_e32 v[40:41], v[26:27]
	v_mov_b64_e32 v[46:47], v[30:31]
	s_andn2_b64 exec, exec, s[6:7]
	s_cbranch_execz .LBB0_1441
